# retention: cache f32->bf16 side job software-pipelined by one chunk step (convert/store at next step top), counted LDS-staging waits
# baseline (speedup 1.0000x reference)
.LBB0_541:
	s_cmp_lt_u32 s21, s92
	s_cselect_b64 s[36:37], -1, 0
	s_cmp_ge_u32 s21, s92
	s_cbranch_scc1 .LBB0_546
	v_add_u32_e32 v82, s33, v2
	v_cmp_lt_i32_e32 vcc, -1, v82
	s_nop 0
	v_mov_b32_e32 v121, 0
	v_mov_b32_e32 v120, 0
	v_mov_b32_e32 v119, 0
	v_mov_b32_e32 v118, 0
	v_mov_b32_e32 v11, 0
	v_mov_b32_e32 v10, 0
	v_mov_b32_e32 v9, 0
	v_mov_b32_e32 v8, 0
	v_mov_b32_e32 v101, 0
	v_mov_b32_e32 v100, 0
	v_mov_b32_e32 v99, 0
	v_mov_b32_e32 v98, 0
	v_mov_b32_e32 v113, 0
	v_mov_b32_e32 v112, 0
	v_mov_b32_e32 v111, 0
	v_mov_b32_e32 v110, 0
	v_mov_b32_e32 v117, 0
	v_mov_b32_e32 v116, 0
	v_mov_b32_e32 v115, 0
	v_mov_b32_e32 v114, 0
	v_mov_b32_e32 v7, 0
	v_mov_b32_e32 v6, 0
	v_mov_b32_e32 v5, 0
	v_mov_b32_e32 v4, 0
	v_mov_b32_e32 v15, 0
	v_mov_b32_e32 v14, 0
	v_mov_b32_e32 v13, 0
	v_mov_b32_e32 v12, 0
	v_mov_b32_e32 v105, 0
	v_mov_b32_e32 v104, 0
	v_mov_b32_e32 v103, 0
	v_mov_b32_e32 v102, 0
	v_mov_b32_e32 v109, 0
	v_mov_b32_e32 v108, 0
	v_mov_b32_e32 v107, 0
	v_mov_b32_e32 v106, 0
	s_and_saveexec_b64 s[72:73], vcc
	s_cbranch_execz .LBB0_544
	v_mov_b64_e32 v[4:5], s[94:95]
	v_mad_u64_u32 v[84:85], vcc, v82, s6, v[4:5]
	v_mov_b64_e32 v[4:5], s[96:97]
	v_mad_u64_u32 v[86:87], vcc, v82, s6, v[4:5]
	v_lshlrev_b64 v[4:5], 1, v[16:17]
	v_lshl_add_u64 v[6:7], v[84:85], 0, v[4:5]
	v_lshl_add_u64 v[8:9], v[86:87], 0, v[4:5]
	v_lshl_add_u64 v[12:13], v[84:85], 0, v[192:193]
	v_lshl_add_u64 v[88:89], v[86:87], 0, v[192:193]
	global_load_dwordx4 v[4:7], v[6:7], off
	s_nop 0
	global_load_dwordx4 v[8:11], v[8:9], off
	s_nop 0
	global_load_dwordx4 v[12:15], v[12:13], off
	s_nop 0
	global_load_dwordx4 v[98:101], v[88:89], off
	v_lshl_add_u64 v[88:89], v[84:85], 0, v[194:195]
	v_lshl_add_u64 v[84:85], v[84:85], 0, v[196:197]
	v_mad_u64_u32 v[82:83], vcc, v82, s6, v[182:183]
	v_lshl_add_u64 v[90:91], v[86:87], 0, v[194:195]
	global_load_dwordx4 v[102:105], v[88:89], off
	global_load_dwordx4 v[110:113], v[90:91], off
	v_lshl_add_u64 v[86:87], v[86:87], 0, v[196:197]
	global_load_dwordx4 v[106:109], v[84:85], off
	global_load_dwordx4 v[114:117], v[86:87], off
	global_load_dwordx4 v[118:121], v[82:83], off

.Lret_nostore:
	s_waitcnt vmcnt(0)
	s_branch .LBB0_559
.LBB0_560:
	v_cndmask_b32_e64 v82, 0, 1, s[26:27]
	v_cmp_ne_u32_e64 s[72:73], 1, v82
	s_andn2_b64 vcc, exec, s[26:27]
	s_cbranch_vccnz .LBB0_562
	s_cmp_eq_u32 s21, 1
	s_cbranch_scc1 .Lcv_noflush
	s_add_i32 s14, s11, 0xfffff000
	s_and_b32 s35, s14, 0x400
	v_or_b32_e32 v82, s35, v223
	s_ashr_i32 s35, s14, 21
	s_mulk_i32 s35, 0x480
	s_ashr_i32 s73, s35, 31
	s_bfe_u32 s14, s14, 0xa000b
	s_add_u32 s72, s35, s14
	s_addc_u32 s73, s73, 0
	s_lshl_b64 s[72:73], s[72:73], 12
	s_add_u32 s72, s8, s72
	s_addc_u32 s73, s9, s73
	v_lshlrev_b32_e32 v90, 1, v82
	s_and_b64 vcc, exec, s[36:37]
	s_cbranch_vccnz .Lcv_w9
	s_waitcnt vmcnt(0)
	s_branch .Lcv_wd
.Lcv_w9:
	s_waitcnt vmcnt(9)
.Lcv_wd:
	v_cvt_pk_bf16_f32 v82, v134, v135
	v_cvt_pk_bf16_f32 v83, v136, v137
	v_cvt_pk_bf16_f32 v84, v130, v131
	v_cvt_pk_bf16_f32 v85, v132, v133
	v_cvt_pk_bf16_f32 v86, v126, v127
	v_cvt_pk_bf16_f32 v87, v128, v129
	v_cvt_pk_bf16_f32 v88, v122, v123
	v_cvt_pk_bf16_f32 v89, v124, v125
	global_store_dwordx4 v90, v[82:85], s[72:73]
	global_store_dwordx4 v90, v[86:89], s[72:73] offset:16
.Lcv_noflush:
	s_ashr_i32 s35, s34, 31
	s_lshl_b64 vcc, s[34:35], 12
	v_lshl_add_u64 v[82:83], v[186:187], 0, vcc
	global_load_dwordx4 v[122:125], v[82:83], off offset:48
	global_load_dwordx4 v[126:129], v[82:83], off offset:32
	global_load_dwordx4 v[130:133], v[82:83], off offset:16
	global_load_dwordx4 v[134:137], v[82:83], off
	s_mov_b32 s14, s11
	s_branch .LBB0_563
.LBB0_562:
	s_waitcnt vmcnt(0)
	s_mov_b32 s14, 0

.LBB0_567:
	s_andn2_b64 vcc, exec, s[36:37]
	s_waitcnt lgkmcnt(0)
	s_barrier
	s_cbranch_vccnz .LBB0_540
	s_nop 3
	v_add_u32_e32 v86, 0, v218
	v_add_u32_e32 v82, 0x10800, v86
	s_waitcnt vmcnt(12)
	ds_write_b128 v217, v[4:7]
	s_waitcnt vmcnt(11)
	ds_write_b128 v217, v[8:11] offset:33792
	s_waitcnt vmcnt(10)
	ds_write_b128 v217, v[12:15] offset:128
	s_waitcnt vmcnt(9)
	ds_write_b128 v217, v[98:101] offset:33920
	s_waitcnt vmcnt(8)
	ds_write_b128 v217, v[102:105] offset:256
	s_waitcnt vmcnt(7)
	ds_write_b128 v217, v[110:113] offset:34048
	s_waitcnt vmcnt(6)
	ds_write_b128 v217, v[106:109] offset:384
	s_waitcnt vmcnt(5)
	ds_write_b128 v217, v[114:117] offset:34176
	s_waitcnt vmcnt(4)
	ds_write_b128 v82, v[118:121]
	v_lshlrev_b32_e32 v82, 16, v118
	v_and_b32_e32 v83, 0xffff0000, v118
	v_mul_f32_e32 v82, v210, v82
	v_mul_f32_e32 v83, v210, v83
	v_cvt_pk_bf16_f32 v82, v82, v83
	v_lshlrev_b32_e32 v83, 16, v119
	v_and_b32_e32 v84, 0xffff0000, v119
	v_mul_f32_e32 v83, v210, v83
	v_mul_f32_e32 v84, v210, v84
	v_cvt_pk_bf16_f32 v83, v83, v84
	v_lshlrev_b32_e32 v84, 16, v120
	v_and_b32_e32 v85, 0xffff0000, v120
	v_mul_f32_e32 v84, v210, v84
	v_mul_f32_e32 v85, v210, v85
	v_cvt_pk_bf16_f32 v84, v84, v85
	v_lshlrev_b32_e32 v85, 16, v121
	v_mul_f32_e32 v85, v210, v85
	v_and_b32_e32 v87, 0xffff0000, v121
	v_add_u32_e32 v86, 0x12800, v86
	v_mul_f32_e32 v87, v210, v87
	v_cvt_pk_bf16_f32 v85, v85, v87
	ds_write_b128 v86, v[82:85]
	s_branch .LBB0_540
.LBB0_569:
	s_andn2_b64 vcc, exec, s[28:29]
	s_cbranch_vccnz .LBB0_523
	s_andn2_b64 vcc, exec, s[26:27]
	s_cbranch_vccnz .Lcv_nofinal
	s_add_i32 s14, s11, 0xfffff000
	s_and_b32 s35, s14, 0x400
	v_or_b32_e32 v82, s35, v223
	s_ashr_i32 s35, s14, 21
	s_mulk_i32 s35, 0x480
	s_ashr_i32 s73, s35, 31
	s_bfe_u32 s14, s14, 0xa000b
	s_add_u32 s72, s35, s14
	s_addc_u32 s73, s73, 0
	s_lshl_b64 s[72:73], s[72:73], 12
	s_add_u32 s72, s8, s72
	s_addc_u32 s73, s9, s73
	v_lshlrev_b32_e32 v90, 1, v82
	s_waitcnt vmcnt(0)
	v_cvt_pk_bf16_f32 v82, v134, v135
	v_cvt_pk_bf16_f32 v83, v136, v137
	v_cvt_pk_bf16_f32 v84, v130, v131
	v_cvt_pk_bf16_f32 v85, v132, v133
	v_cvt_pk_bf16_f32 v86, v126, v127
	v_cvt_pk_bf16_f32 v87, v128, v129
	v_cvt_pk_bf16_f32 v88, v122, v123
	v_cvt_pk_bf16_f32 v89, v124, v125
	global_store_dwordx4 v90, v[82:85], s[72:73]
	global_store_dwordx4 v90, v[86:89], s[72:73] offset:16
.Lcv_nofinal:
	v_lshlrev_b32_e32 v2, 11, v1
	s_waitcnt vmcnt(8)
	v_lshl_add_u64 v[4:5], s[74:75], 0, v[2:3]
	s_lshl_b32 s14, s7, 2
	v_lshl_add_u64 v[4:5], v[4:5], 0, s[14:15]
	v_lshlrev_b32_e32 v2, 2, v219
	v_lshl_add_u64 v[4:5], v[4:5], 0, v[2:3]
	s_mov_b32 s1, 0x10000
	s_waitcnt vmcnt(7)
	v_add_co_u32_e32 v8, vcc, s1, v4
	s_mov_b64 s[2:3], 0x10000
	s_nop 0
	v_addc_co_u32_e32 v9, vcc, 0, v5, vcc
	global_store_dwordx4 v[4:5], v[66:69], off
	global_store_dwordx4 v[4:5], v[70:73], off offset:32
	global_store_dwordx4 v[4:5], v[74:77], off offset:64
	global_store_dwordx4 v[4:5], v[78:81], off offset:96
	v_lshl_add_u64 v[6:7], v[4:5], 0, s[2:3]
	global_store_dwordx4 v[8:9], v[50:53], off
	global_store_dwordx4 v[6:7], v[54:57], off offset:32
	global_store_dwordx4 v[6:7], v[58:61], off offset:64
	global_store_dwordx4 v[6:7], v[62:65], off offset:96
	global_store_dwordx4 v[4:5], v[34:37], off offset:128
	global_store_dwordx4 v[4:5], v[38:41], off offset:160
	global_store_dwordx4 v[4:5], v[42:45], off offset:192
	global_store_dwordx4 v[4:5], v[46:49], off offset:224
	global_store_dwordx4 v[6:7], v[18:21], off offset:128
	global_store_dwordx4 v[6:7], v[22:25], off offset:160
	global_store_dwordx4 v[6:7], v[26:29], off offset:192
	global_store_dwordx4 v[6:7], v[30:33], off offset:224
	s_branch .LBB0_523
